# v28 (no per-block s_setprio flips) + one static s_setprio 1 for waves 0-3 at kernel start
# speedup vs baseline: 1.0084x; 1.0084x over previous
; __global__ void __launch_bounds__(512, 2) mega_fwd(Args a) {
;     ...
;   const int tid = threadIdx.x, lane = tid & 63, wave = __builtin_amdgcn_readfirstlane(tid >> 6);
;   const int G = gridDim.x, bx = blockIdx.x;
;   const int gw = bx * 8 + wave, NGW = G * 8;
.LBB0_5:
	s_or_b64 exec, exec, s[2:3]
	s_lshr_b32 s3, s6, 6
	s_lshl_b32 s2, s68, 3
	s_add_i32 s96, s3, s2
	s_lshl_b32 s78, s82, 3
	s_cmp_ge_u32 s3, 4
	s_cbranch_scc1 .Lprio_static_skip
	s_setprio 1
